# prologue de-serialisation in P0: the row loop's first row and norm-gain loads issued ahead of the barrier
# baseline (speedup 1.0000x reference)
; #define GAS __attribute__((address_space(1)))
; #define LAS __attribute__((address_space(3)))
; __device__ __forceinline__ void p0_prologue(const Args& a, LAS unsigned char* lds, int vcu, int G, int tid, int lane, int wave) {
;     ...
;     __syncthreads();
;     const GAS f32x4* gp = (const GAS f32x4*)n1g + lane;
;     f32x4 gv[4];
; #pragma unroll
;     for (int j = 0; j < 4; ++j) gv[j] = gp[64 * j];
;     f32x4 nv[4];
;     if (gw < T) { const GAS f32x4* xr0 = (const GAS f32x4*)(x + (size_t)gw * DM) + lane;
; #pragma unroll
;         for (int j = 0; j < 4; ++j) nv[j] = xr0[64 * j]; }
;     for (int m = gw; m < T; m += NGW) {
;         f32x4 v[4]; float s2 = 0.f;
; #pragma unroll
;         for (int j = 0; j < 4; ++j) { v[j] = nv[j]; s2 += (v[j].x * v[j].x + v[j].y * v[j].y) + (v[j].z * v[j].z + v[j].w * v[j].w); }
;         if (m + NGW < T) { const GAS f32x4* xr = (const GAS f32x4*)(x + (size_t)(m + NGW) * DM) + lane;
; #pragma unroll
;             for (int j = 0; j < 4; ++j) nv[j] = xr[64 * j]; }
;         const float rstd = 1.0f / sqrtf(wave_sum(s2) * (1.f / DM) + EPS);
;     ...
;         for (int h = 0; h < 8; ++h) { float acc = 0.f;
; #pragma unroll
;             for (int j = 0; j < 4; ++j) { const f32x4 w = *(const LAS f32x4*)(wf + h * 1024 + 256 * j + 4 * lane); acc += (v[j].x * w.x + v[j].y * w.y) + (v[j].z * w.z + v[j].w * w.w); }
;             f[h] = wave_sum(acc); }
.LBB0_54:
	s_or_b64 exec, exec, s[6:7]
	s_ashr_i32 s63, s62, 31
	s_lshl_b64 s[0:1], s[62:63], 12
	s_add_u32 s0, s36, s0
	v_lshlrev_b32_e32 v36, 4, v188
	s_addc_u32 s1, s37, s1
	global_load_dwordx4 v[2:5], v36, s[38:39]
	global_load_dwordx4 v[6:9], v36, s[38:39] offset:1024
	global_load_dwordx4 v[10:13], v36, s[38:39] offset:2048
	global_load_dwordx4 v[14:17], v36, s[38:39] offset:3072
	global_load_dwordx4 v[174:177], v36, s[0:1] nt
	global_load_dwordx4 v[170:173], v36, s[0:1] offset:1024 nt
	global_load_dwordx4 v[166:169], v36, s[0:1] offset:2048 nt
	global_load_dwordx4 v[162:165], v36, s[0:1] offset:3072 nt
	s_cmp_lt_i32 s62, 0x8000
	s_waitcnt lgkmcnt(0)
	s_barrier
	s_cbranch_scc0 .LBB0_61
	v_mbcnt_lo_u32_b32 v1, -1, 0
	v_mbcnt_hi_u32_b32 v18, -1, v1
	v_and_b32_e32 v1, 64, v18
	v_add_u32_e32 v19, 64, v1
	v_xor_b32_e32 v1, 1, v18
	v_cmp_lt_i32_e32 vcc, v1, v19
	v_xor_b32_e32 v20, 2, v18
	s_lshl_b64 s[18:19], s[62:63], 11
	v_cndmask_b32_e32 v1, v18, v1, vcc
	v_cmp_lt_i32_e32 vcc, v20, v19
	v_mov_b32_e32 v37, 0
	s_add_u32 s18, s26, s18
	v_cndmask_b32_e32 v20, v18, v20, vcc
	v_lshlrev_b32_e32 v189, 2, v20
	v_xor_b32_e32 v20, 4, v18
	v_cmp_lt_i32_e32 vcc, v20, v19
	v_mov_b32_e32 v35, v37
	s_addc_u32 s19, s27, s19
	v_cndmask_b32_e32 v20, v18, v20, vcc
	v_lshlrev_b32_e32 v190, 2, v20
	v_xor_b32_e32 v20, 8, v18
	v_cmp_lt_i32_e32 vcc, v20, v19
	v_lshl_add_u64 v[180:181], s[18:19], 0, v[34:35]
	s_add_i32 s18, s62, s34
	v_cndmask_b32_e32 v20, v18, v20, vcc
	v_lshlrev_b32_e32 v191, 2, v20
	v_xor_b32_e32 v20, 16, v18
	v_cmp_lt_i32_e32 vcc, v20, v19
	s_ashr_i32 s35, s34, 31
	s_ashr_i32 s19, s18, 31
	v_cndmask_b32_e32 v20, v18, v20, vcc
	v_lshlrev_b32_e32 v192, 2, v20
	v_xor_b32_e32 v20, 32, v18
	v_cmp_lt_i32_e32 vcc, v20, v19
	s_lshl_b64 s[40:41], s[34:35], 11
	s_lshl_b64 s[18:19], s[18:19], 12
	v_cndmask_b32_e32 v18, v18, v20, vcc
	v_lshlrev_b32_e32 v193, 2, v18
	v_add_u32_e32 v18, 0, v36
	s_add_u32 s18, s36, s18
	v_add_u32_e32 v142, 0x12000, v18
	v_lshlrev_b32_e32 v18, 2, v188
	v_mov_b32_e32 v19, v37
	s_addc_u32 s19, s37, s19
	v_lshl_add_u64 v[178:179], s[50:51], 0, v[18:19]
	ds_read_b128 v[18:21], v142
	ds_read_b128 v[22:25], v142 offset:1024
	ds_read_b128 v[26:29], v142 offset:2048
	ds_read_b128 v[30:33], v142 offset:3072
	v_lshl_add_u64 v[182:183], s[18:19], 0, v[36:37]
	ds_read_b128 v[34:37], v142 offset:4096
	ds_read_b128 v[38:41], v142 offset:5120
	ds_read_b128 v[42:45], v142 offset:6144
	ds_read_b128 v[46:49], v142 offset:7168
	ds_read_b128 v[50:53], v142 offset:8192
	ds_read_b128 v[54:57], v142 offset:9216
	ds_read_b128 v[58:61], v142 offset:10240
	ds_read_b128 v[62:65], v142 offset:11264
	ds_read_b128 v[66:69], v142 offset:12288
	ds_read_b128 v[70:73], v142 offset:13312
	ds_read_b128 v[74:77], v142 offset:14336
	ds_read_b128 v[78:81], v142 offset:15360
	ds_read_b128 v[82:85], v142 offset:16384
	ds_read_b128 v[86:89], v142 offset:17408
	ds_read_b128 v[90:93], v142 offset:18432
	ds_read_b128 v[94:97], v142 offset:19456
	ds_read_b128 v[98:101], v142 offset:20480
	ds_read_b128 v[102:105], v142 offset:21504
	ds_read_b128 v[106:109], v142 offset:22528
	ds_read_b128 v[110:113], v142 offset:23552
	ds_read_b128 v[114:117], v142 offset:24576
	ds_read_b128 v[118:121], v142 offset:25600
	ds_read_b128 v[122:125], v142 offset:26624
	ds_read_b128 v[126:129], v142 offset:27648
	ds_read_b128 v[130:133], v142 offset:28672
	ds_read_b128 v[134:137], v142 offset:29696
	ds_read_b128 v[138:141], v142 offset:30720
	ds_read_b128 v[142:145], v142 offset:31744
	s_mov_b32 s39, 0
	v_lshlrev_b32_e32 v1, 2, v1
	v_cmp_gt_u32_e64 s[0:1], 8, v188
	v_cmp_eq_u32_e64 s[16:17], 7, v188
	v_cmp_eq_u32_e64 s[4:5], 6, v188
	v_cmp_eq_u32_e64 s[6:7], 5, v188
	v_cmp_eq_u32_e64 s[8:9], 4, v188
	v_cmp_eq_u32_e64 s[10:11], 3, v188
	v_cmp_eq_u32_e64 s[12:13], 2, v188
	v_cmp_eq_u32_e64 s[14:15], 1, v188
	s_lshl_b64 s[46:47], s[34:35], 12
	v_mov_b32_e32 v194, 0x358637bd
	s_mov_b32 s33, 0xf800000
	v_mov_b32_e32 v195, 0x260
	s_mov_b32 s35, 0xbfb8aa3b
	s_mov_b32 s54, 0xb2a5705f
	s_mov_b32 s55, 0x42ce8ed0
	s_mov_b32 s56, 0xc2b17218
	s_mov_b32 s57, 0x7f800000
	s_mov_b32 s58, 0x3f2aaaab
	v_mov_b32_e32 v196, 0x3ecc95a3
	s_mov_b32 s59, 0x3f317218
	s_mov_b32 s63, 0x33800000
	v_mov_b32_e32 v197, 0x7f800000
	v_mov_b32_e32 v184, 0x3f317218
	s_waitcnt vmcnt(3)
	v_mov_b64_e32 v[158:159], v[174:175]
	s_waitcnt vmcnt(2)
	v_mov_b64_e32 v[154:155], v[170:171]
	s_waitcnt vmcnt(1)
	v_mov_b64_e32 v[150:151], v[166:167]
	s_waitcnt vmcnt(0)
	v_mov_b64_e32 v[146:147], v[162:163]
	v_mov_b64_e32 v[148:149], v[164:165]
	v_mov_b64_e32 v[152:153], v[168:169]
	v_mov_b64_e32 v[156:157], v[172:173]
	v_mov_b64_e32 v[160:161], v[176:177]
	s_branch .LBB0_57
